# plus ln_rows (after output projection) modulate step: modulation-vector groups 2 and 4 requested together with groups 1 and 3 into spare registers
# baseline (speedup 1.0000x reference)
; __device__ __forceinline__ float bflo(unsigned u) { return __uint_as_float(u << 16); }
; __device__ __forceinline__ float bfhi(unsigned u) { return __uint_as_float(u & 0xffff0000u); }
; __device__ __forceinline__ void ln_rows(const Params& P, const float* gam, const float* bet, const float* modU, int shidx, bool writeU, bool writeOut, int nsplit, bool skipctx) {
;     ...
;         f32x4 v[8]; float s = 0.f;
; #pragma unroll
;         for (int j = 0; j < 8; ++j) { const int c = ((j >> 1) * 64 + lane) * 8 + (j & 1) * 4;
;             if (!pf) {
;                 f32x4 a = *(const f32x4*)(X + (size_t)r * D + c) * ALPHA; const float* pp = (const float*)(P.ws + WS_SCTX) + ((size_t)b * 256 + p) * D + c;
;                 for (int q = 0; q < nsplit; ++q) a += *(const f32x4*)(pp + (size_t)q * 512 * D);
;                 v[j] = a; }
;             else { const unsigned t0 = (j & 1) ? ct[j >> 1].z : ct[j >> 1].x, t1 = (j & 1) ? ct[j >> 1].w : ct[j >> 1].y;
;                 v[j] = cx[j] * ALPHA + (f32x4){bflo(t0), bfhi(t0), bflo(t1), bfhi(t1)}; }
;             s += (v[j][0] + v[j][1]) + (v[j][2] + v[j][3]); }
;         const float mean = wave_sum(s) * (1.f / D); float s2 = 0.f;
; #pragma unroll
;         for (int j = 0; j < 8; ++j) { v[j] = v[j] - mean; s2 += (v[j][0] * v[j][0] + v[j][1] * v[j][1]) + (v[j][2] * v[j][2] + v[j][3] * v[j][3]); }
;         const float rstd = __builtin_amdgcn_rsqf(wave_sum(s2) * (1.f / D) + 1e-5f);
.LBB0_1161:
	s_or_b64 exec, exec, s[8:9]
	v_add_f32_e32 v1, v116, v117
	v_add_f32_e32 v149, v118, v119
	v_add_f32_e32 v1, v1, v149
	v_add_f32_e32 v149, v120, v121
	v_add_f32_e32 v151, v122, v123
	v_add_f32_e32 v1, 0, v1
	v_add_f32_e32 v149, v149, v151
	v_add_f32_e32 v1, v1, v149
	v_add_f32_e32 v149, v124, v125
	v_add_f32_e32 v151, v126, v127
	v_add_f32_e32 v149, v149, v151
	v_add_f32_e32 v1, v1, v149
	v_add_f32_e32 v149, v128, v129
	v_add_f32_e32 v151, v130, v131
	v_add_f32_e32 v149, v149, v151
	v_add_f32_e32 v1, v1, v149
	v_add_f32_e32 v149, v132, v133
	v_add_f32_e32 v151, v134, v135
	v_add_f32_e32 v149, v149, v151
	v_add_f32_e32 v1, v1, v149
	v_add_f32_e32 v149, v140, v141
	v_add_f32_e32 v151, v142, v143
	v_add_f32_e32 v149, v149, v151
	v_add_f32_e32 v1, v1, v149
	v_add_f32_e32 v149, v136, v137
	v_add_f32_e32 v151, v138, v139
	v_mov_b32_e32 v182, v145
	v_mov_b32_e32 v183, v146
	v_mov_b32_e32 v184, v144
	v_mov_b32_e32 v185, v147
	v_add_f32_e32 v149, v149, v151
	v_pk_add_f32 v[182:183], v[182:183], v[184:185]
	v_add_f32_e32 v1, v1, v149
	v_add_f32_e32 v149, v182, v183
	v_add_f32_e32 v1, v1, v149
	v_cmp_lt_i32_e32 vcc, s92, v188
	v_mov_b32_e32 v177, v3
	v_add_f32_dpp v1, v1, v1 row_ror:8 row_mask:0xf bank_mask:0xf bound_ctrl:1
	v_mov_b32_e32 v149, v3
	v_mov_b32_e32 v151, v3
	v_add_f32_dpp v1, v1, v1 row_ror:4 row_mask:0xf bank_mask:0xf bound_ctrl:1
	s_nop 1
	v_add_f32_dpp v1, v1, v1 row_ror:2 row_mask:0xf bank_mask:0xf bound_ctrl:1
	s_nop 1
	v_add_f32_dpp v1, v1, v1 row_ror:1 row_mask:0xf bank_mask:0xf bound_ctrl:1
	s_nop 0
	v_readlane_b32 s10, v1, 16
	v_readlane_b32 s11, v1, 48
	v_readlane_b32 s8, v1, 0
	v_readlane_b32 s9, v1, 32
	v_mov_b32_e32 v182, s10
	v_mov_b32_e32 v183, s11
	v_pk_add_f32 v[182:183], s[8:9], v[182:183]
	s_nop 0
	v_add_f32_e32 v1, v182, v183
	v_fmamk_f32 v117, v1, 0xba000000, v117
	v_fmamk_f32 v121, v1, 0xba000000, v121
	v_fmamk_f32 v183, v1, 0xba000000, v119
	v_fmac_f32_e32 v116, 0xba000000, v1
	v_fmamk_f32 v191, v1, 0xba000000, v123
	v_fmamk_f32 v190, v1, 0xba000000, v122
	v_fmac_f32_e32 v120, 0xba000000, v1
	v_mov_b32_e32 v122, v117
	v_mov_b32_e32 v123, v121
	v_fmamk_f32 v182, v1, 0xba000000, v118
	v_mov_b32_e32 v118, v116
	v_mov_b32_e32 v119, v120
	v_pk_mul_f32 v[122:123], v[122:123], v[122:123]
	v_mov_b32_e32 v184, v183
	v_mov_b32_e32 v185, v191
	v_pk_fma_f32 v[118:119], v[118:119], v[118:119], v[122:123]
	v_mov_b32_e32 v122, v182
	v_mov_b32_e32 v123, v190
	v_pk_mul_f32 v[184:185], v[184:185], v[184:185]
	v_fmamk_f32 v195, v1, 0xba000000, v125
	v_pk_fma_f32 v[122:123], v[122:123], v[122:123], v[184:185]
	v_fmamk_f32 v194, v1, 0xba000000, v124
	v_pk_add_f32 v[118:119], v[118:119], v[122:123]
	v_fmamk_f32 v127, v1, 0xba000000, v127
	v_fmac_f32_e32 v126, 0xba000000, v1
	v_pk_add_f32 v[118:119], v[118:119], v[118:119] op_sel_hi:[0,1]
	v_pk_mul_f32 v[122:123], v[126:127], v[126:127]
	v_pk_mul_f32 v[124:125], v[194:195], v[194:195]
	v_fmamk_f32 v214, v1, 0xba000000, v128
	v_pk_mov_b32 v[184:185], v[124:125], v[122:123] op_sel:[1,0]
	v_mov_b32_e32 v125, v123
	v_fmamk_f32 v215, v1, 0xba000000, v129
	v_fmac_f32_e32 v130, 0xba000000, v1
	v_mul_f32_e32 v118, v214, v214
	v_pk_add_f32 v[122:123], v[184:185], v[124:125]
	v_fmamk_f32 v131, v1, 0xba000000, v131
	v_pk_fma_f32 v[124:125], v[214:215], v[214:215], v[118:119] op_sel_hi:[1,1,0]
	v_mul_f32_e32 v118, v130, v130
	v_pk_add_f32 v[122:123], v[122:123], v[122:123] op_sel_hi:[0,1]
	v_pk_fma_f32 v[128:129], v[130:131], v[130:131], v[118:119] op_sel_hi:[1,1,0]
	v_fmamk_f32 v217, v1, 0xba000000, v135
	v_fmamk_f32 v216, v1, 0xba000000, v134
	v_fmamk_f32 v133, v1, 0xba000000, v133
	v_fmac_f32_e32 v132, 0xba000000, v1
	v_mul_f32_e32 v124, v132, v132
	v_mul_f32_e32 v128, v133, v133
	v_mul_f32_e32 v122, v216, v216
	v_mul_f32_e32 v118, v217, v217
	v_pk_add_f32 v[124:125], v[124:125], v[128:129]
	v_pk_add_f32 v[118:119], v[122:123], v[118:119]
	v_fmamk_f32 v141, v1, 0xba000000, v141
	v_pk_add_f32 v[118:119], v[124:125], v[118:119]
	v_fmamk_f32 v140, v1, 0xba000000, v140
	v_fmamk_f32 v143, v1, 0xba000000, v143
	v_fmac_f32_e32 v142, 0xba000000, v1
	v_pk_add_f32 v[124:125], v[118:119], v[118:119] op_sel_hi:[0,1]
	v_pk_mul_f32 v[118:119], v[142:143], v[142:143]
	v_pk_mul_f32 v[122:123], v[140:141], v[140:141]
	v_fmac_f32_e32 v138, 0xba000000, v1
	v_pk_mov_b32 v[128:129], v[122:123], v[118:119] op_sel:[1,0]
	v_mov_b32_e32 v123, v119
	v_pk_add_f32 v[118:119], v[128:129], v[122:123]
	v_fmamk_f32 v139, v1, 0xba000000, v139
	v_pk_add_f32 v[128:129], v[118:119], v[118:119] op_sel_hi:[0,1]
	v_fmamk_f32 v118, v1, 0xba000000, v136
	v_fmamk_f32 v119, v1, 0xba000000, v137
	v_mul_f32_e32 v122, v118, v118
	v_pk_fma_f32 v[134:135], v[118:119], v[118:119], v[122:123] op_sel_hi:[1,1,0]
	v_mul_f32_e32 v122, v138, v138
	v_pk_fma_f32 v[136:137], v[138:139], v[138:139], v[122:123] op_sel_hi:[1,1,0]
	v_fmamk_f32 v123, v1, 0xba000000, v147
	v_fmamk_f32 v122, v1, 0xba000000, v146
	v_fmamk_f32 v145, v1, 0xba000000, v145
	v_fmac_f32_e32 v144, 0xba000000, v1
	v_mul_f32_e32 v134, v144, v144
	v_mul_f32_e32 v136, v145, v145
	v_mul_f32_e32 v128, v122, v122
	v_mul_f32_e32 v124, v123, v123
	v_pk_add_f32 v[134:135], v[134:135], v[136:137]
	v_pk_add_f32 v[124:125], v[128:129], v[124:125]
	s_nop 0
	v_pk_add_f32 v[124:125], v[134:135], v[124:125]
	s_nop 0
	v_add_f32_e32 v1, v124, v125
	s_nop 1
	v_add_f32_dpp v1, v1, v1 row_ror:8 row_mask:0xf bank_mask:0xf bound_ctrl:1
	s_nop 1
	v_add_f32_dpp v1, v1, v1 row_ror:4 row_mask:0xf bank_mask:0xf bound_ctrl:1
	s_nop 1
	v_add_f32_dpp v1, v1, v1 row_ror:2 row_mask:0xf bank_mask:0xf bound_ctrl:1
	s_nop 1
	v_add_f32_dpp v1, v1, v1 row_ror:1 row_mask:0xf bank_mask:0xf bound_ctrl:1
; __device__ __forceinline__ unsigned pk2(float lo, float hi) { unsigned r; asm("v_cvt_pk_bf16_f32 %0, %1, %2" : "=v"(r) : "v"(lo), "v"(hi)); return r; }
; __device__ __forceinline__ void ln_rows(const Params& P, const float* gam, const float* bet, const float* modU, int shidx, bool writeU, bool writeOut, int nsplit, bool skipctx) {
;     ...
;         const float rstd = __builtin_amdgcn_rsqf(wave_sum(s2) * (1.f / D) + 1e-5f);
;         const float* mv = modU + (size_t)(isctx ? 2 : b) * (6 * D) + (size_t)shidx * D;
; #pragma unroll
;         for (int jj = 0; jj < 4; ++jj) { const int c = (jj * 64 + lane) * 8;
;             const f32x4 y0 = v[2 * jj] * rstd * gv[2 * jj] + bv[2 * jj], y1 = v[2 * jj + 1] * rstd * gv[2 * jj + 1] + bv[2 * jj + 1];
;             if (!writeOut) { *(f32x4*)(X + (size_t)r * D + c) = y0; *(f32x4*)(X + (size_t)r * D + c + 4) = y1; }
;             if (writeU) { const f32x4 sh0 = *(const f32x4*)(mv + c), sc0 = *(const f32x4*)(mv + D + c), sh1 = *(const f32x4*)(mv + c + 4), sc1 = *(const f32x4*)(mv + D + c + 4);
;                 const f32x4 z0 = y0 * (1.f + sc0) + sh0, z1 = y1 * (1.f + sc1) + sh1;
;                 u32x4 o; o.x = pk2(z0[0], z0[1]); o.y = pk2(z0[2], z0[3]); o.z = pk2(z1[0], z1[1]); o.w = pk2(z1[2], z1[3]); *(u32x4*)(U + (size_t)r * D + c) = o; }
	s_nop 0
	v_readlane_b32 s10, v1, 16
	v_readlane_b32 s11, v1, 48
	v_readlane_b32 s8, v1, 0
	v_readlane_b32 s9, v1, 32
	v_mov_b32_e32 v124, s10
	v_mov_b32_e32 v125, s11
	v_pk_add_f32 v[124:125], s[8:9], v[124:125]
	s_mov_b64 s[8:9], 0x2000
	v_add_f32_e32 v1, v124, v125
	v_fmamk_f32 v1, v1, 0x3a000000, v224
	v_rsq_f32_e32 v128, v1
	v_cndmask_b32_e32 v1, 2, v186, vcc
	v_mul_hi_i32_i24_e32 v125, 0xc000, v1
	v_mul_i32_i24_e32 v124, 0xc000, v1
	v_pk_mul_f32 v[116:117], v[116:117], v[128:129] op_sel_hi:[1,0]
	v_lshl_add_u64 v[124:125], s[14:15], 0, v[124:125]
	v_pk_mul_f32 v[136:137], v[182:183], v[128:129] op_sel_hi:[1,0]
	v_pk_fma_f32 v[182:183], v[8:9], v[116:117], v[16:17]
	v_pk_mul_f32 v[116:117], v[120:121], v[128:129] op_sel_hi:[1,0]
	v_pk_mul_f32 v[120:121], v[190:191], v[128:129] op_sel_hi:[1,0]
	v_lshl_add_u64 v[134:135], v[124:125], 0, s[8:9]
	v_pk_fma_f32 v[184:185], v[10:11], v[136:137], v[18:19]
	v_pk_fma_f32 v[188:189], v[6:7], v[120:121], v[14:15]
	v_lshl_add_u64 v[120:121], v[180:181], 0, v[2:3]
	v_pk_fma_f32 v[186:187], v[4:5], v[116:117], v[12:13]
	global_store_dwordx4 v[120:121], v[182:185], off
	global_store_dwordx4 v[120:121], v[186:189], off offset:16
	v_lshl_add_u64 v[116:117], v[134:135], 0, v[2:3]
	global_load_dwordx4 v[190:193], v[116:117], off
	v_lshl_add_u64 v[136:137], v[124:125], 0, v[2:3]
	global_load_dwordx4 v[202:205], v[136:137], off
	global_load_dwordx4 v[206:209], v[116:117], off offset:16
	global_load_dwordx4 v[210:213], v[136:137], off offset:16
	v_lshl_add_u64 v[234:235], v[134:135], 0, v[176:177]
	global_load_dwordx4 v[238:241], v[234:235], off offset:16
	global_load_dwordx4 v[234:237], v[234:235], off
	global_load_dwordx4 v[244:247], v[136:137], off offset:2048
	global_load_dwordx2 v[248:249], v[136:137], off offset:2064
	global_load_dwordx2 v[254:255], v[136:137], off offset:2072
	v_lshlrev_b64 v[116:117], 12, v[178:179]
	v_lshl_add_u64 v[116:117], v[154:155], 0, v[116:117]
	v_pk_mul_f32 v[126:127], v[126:127], v[128:129] op_sel_hi:[1,0]
	v_pk_mul_f32 v[130:131], v[130:131], v[128:129] op_sel_hi:[1,0]
	v_pk_mul_f32 v[122:123], v[122:123], v[128:129] op_sel_hi:[1,0]
	v_pk_mul_f32 v[118:119], v[118:119], v[128:129] op_sel_hi:[1,0]
	s_and_b64 s[8:9], exec, s[18:19]
	v_pk_fma_f32 v[118:119], v[56:57], v[118:119], v[64:65]
	s_or_b64 s[16:17], s[8:9], s[16:17]
	s_waitcnt vmcnt(8)
	v_pk_add_f32 v[146:147], v[192:193], 1.0 op_sel_hi:[1,0]
	v_pk_add_f32 v[178:179], v[190:191], 1.0 op_sel_hi:[1,0]
	s_waitcnt vmcnt(7)
	v_pk_fma_f32 v[146:147], v[146:147], v[184:185], v[204:205]
	s_waitcnt vmcnt(6)
	v_pk_add_f32 v[184:185], v[206:207], 1.0 op_sel_hi:[1,0]
	v_pk_fma_f32 v[178:179], v[178:179], v[182:183], v[202:203]
	v_pk_add_f32 v[182:183], v[208:209], 1.0 op_sel_hi:[1,0]
	s_waitcnt vmcnt(5)
	v_pk_fma_f32 v[184:185], v[184:185], v[186:187], v[210:211]
	v_pk_fma_f32 v[188:189], v[182:183], v[188:189], v[212:213]
	v_cvt_pk_bf16_f32 v182, v178, v179
	v_cvt_pk_bf16_f32 v183, v146, v147
	v_cvt_pk_bf16_f32 v184, v184, v185
	v_pk_mul_f32 v[146:147], v[194:195], v[128:129] op_sel_hi:[1,0]
	v_cvt_pk_bf16_f32 v185, v188, v189
	global_store_dwordx4 v[116:117], v[182:185], off
	v_pk_fma_f32 v[188:189], v[22:23], v[130:131], v[30:31]
	s_nop 0
	v_pk_fma_f32 v[184:185], v[26:27], v[126:127], v[34:35]
	v_pk_fma_f32 v[182:183], v[24:25], v[146:147], v[32:33]
	v_pk_mul_f32 v[126:127], v[214:215], v[128:129] op_sel_hi:[1,0]
	v_pk_mul_f32 v[146:147], v[142:143], v[128:129] op_sel_hi:[1,0]
	v_pk_fma_f32 v[186:187], v[20:21], v[126:127], v[28:29]
	global_store_dwordx4 v[120:121], v[182:185], off offset:2048
	global_store_dwordx4 v[120:121], v[186:189], off offset:2064
	v_lshl_add_u64 v[120:121], v[134:135], 0, v[176:177]
	v_pk_mul_f32 v[120:121], v[132:133], v[128:129] op_sel_hi:[1,0]
	v_pk_mul_f32 v[126:127], v[216:217], v[128:129] op_sel_hi:[1,0]
	v_pk_fma_f32 v[130:131], v[40:41], v[120:121], v[48:49]
	v_pk_mul_f32 v[136:137], v[140:141], v[128:129] op_sel_hi:[1,0]
	v_pk_fma_f32 v[132:133], v[42:43], v[126:127], v[50:51]
	s_waitcnt vmcnt(3)
; __device__ __forceinline__ unsigned pk2(float lo, float hi) { unsigned r; asm("v_cvt_pk_bf16_f32 %0, %1, %2" : "=v"(r) : "v"(lo), "v"(hi)); return r; }
; __device__ __forceinline__ void ln_rows(const Params& P, const float* gam, const float* bet, const float* modU, int shidx, bool writeU, bool writeOut, int nsplit, bool skipctx) {
;     ...
;         for (int jj = 0; jj < 4; ++jj) { const int c = (jj * 64 + lane) * 8;
;             const f32x4 y0 = v[2 * jj] * rstd * gv[2 * jj] + bv[2 * jj], y1 = v[2 * jj + 1] * rstd * gv[2 * jj + 1] + bv[2 * jj + 1];
;             if (!writeOut) { *(f32x4*)(X + (size_t)r * D + c) = y0; *(f32x4*)(X + (size_t)r * D + c + 4) = y1; }
;             if (writeU) { const f32x4 sh0 = *(const f32x4*)(mv + c), sc0 = *(const f32x4*)(mv + D + c), sh1 = *(const f32x4*)(mv + c + 4), sc1 = *(const f32x4*)(mv + D + c + 4);
;                 const f32x4 z0 = y0 * (1.f + sc0) + sh0, z1 = y1 * (1.f + sc1) + sh1;
;                 u32x4 o; o.x = pk2(z0[0], z0[1]); o.y = pk2(z0[2], z0[3]); o.z = pk2(z1[0], z1[1]); o.w = pk2(z1[2], z1[3]); *(u32x4*)(U + (size_t)r * D + c) = o; }
	v_pk_add_f32 v[120:121], v[236:237], 1.0 op_sel_hi:[1,0]
	v_pk_add_f32 v[142:143], v[238:239], 1.0 op_sel_hi:[1,0]
	v_pk_add_f32 v[126:127], v[234:235], 1.0 op_sel_hi:[1,0]
	v_pk_add_f32 v[140:141], v[240:241], 1.0 op_sel_hi:[1,0]
	v_pk_fma_f32 v[120:121], v[184:185], v[120:121], v[246:247]
	v_pk_fma_f32 v[142:143], v[186:187], v[142:143], v[248:249]
	v_pk_fma_f32 v[126:127], v[182:183], v[126:127], v[244:245]
	v_pk_fma_f32 v[178:179], v[188:189], v[140:141], v[254:255]
	v_cvt_pk_bf16_f32 v140, v126, v127
	v_cvt_pk_bf16_f32 v141, v120, v121
	v_cvt_pk_bf16_f32 v142, v142, v143
	v_lshl_add_u64 v[120:121], v[180:181], 0, v[148:149]
	v_cvt_pk_bf16_f32 v143, v178, v179
	global_store_dwordx4 v[116:117], v[140:143], off offset:1024
	v_pk_mul_f32 v[126:127], v[144:145], v[128:129] op_sel_hi:[1,0]
	s_nop 0
	v_pk_fma_f32 v[142:143], v[38:39], v[146:147], v[46:47]
	v_pk_fma_f32 v[140:141], v[36:37], v[136:137], v[44:45]
	global_store_dwordx4 v[120:121], v[130:133], off
	global_store_dwordx4 v[120:121], v[140:143], off offset:16
	v_lshl_add_u64 v[120:121], v[134:135], 0, v[148:149]
	global_load_dwordx4 v[182:185], v[120:121], off
	global_load_dwordx4 v[186:189], v[120:121], off offset:16
	v_lshl_add_u64 v[120:121], v[124:125], 0, v[148:149]
	global_load_dwordx4 v[190:193], v[120:121], off
	global_load_dwordx4 v[202:205], v[120:121], off offset:16
	v_lshl_add_u64 v[234:235], v[134:135], 0, v[150:151]
	global_load_dwordx4 v[238:241], v[234:235], off offset:16
	global_load_dwordx4 v[234:237], v[234:235], off
	v_lshl_add_u64 v[244:245], v[124:125], 0, v[150:151]
	global_load_dwordx2 v[248:249], v[244:245], off offset:16
	global_load_dwordx2 v[254:255], v[244:245], off offset:24
	global_load_dwordx4 v[244:247], v[244:245], off
	v_pk_mul_f32 v[120:121], v[138:139], v[128:129] op_sel_hi:[1,0]
	v_pk_fma_f32 v[128:129], v[54:55], v[122:123], v[62:63]
	v_lshl_add_u64 v[136:137], v[180:181], 0, v[150:151]
	v_lshl_add_u64 v[134:135], v[134:135], 0, v[150:151]
	v_pk_fma_f32 v[120:121], v[58:59], v[120:121], v[66:67]
	v_pk_fma_f32 v[126:127], v[52:53], v[126:127], v[60:61]
	s_waitcnt vmcnt(8)
	v_pk_add_f32 v[122:123], v[184:185], 1.0 op_sel_hi:[1,0]
	v_pk_add_f32 v[138:139], v[182:183], 1.0 op_sel_hi:[1,0]
	s_waitcnt vmcnt(7)
	v_pk_add_f32 v[146:147], v[186:187], 1.0 op_sel_hi:[1,0]
	v_pk_add_f32 v[144:145], v[188:189], 1.0 op_sel_hi:[1,0]
	s_waitcnt vmcnt(6)
	v_pk_fma_f32 v[122:123], v[132:133], v[122:123], v[192:193]
	v_pk_fma_f32 v[130:131], v[130:131], v[138:139], v[190:191]
	s_waitcnt vmcnt(5)
	v_pk_fma_f32 v[132:133], v[140:141], v[146:147], v[202:203]
	v_pk_fma_f32 v[138:139], v[142:143], v[144:145], v[204:205]
	v_cvt_pk_bf16_f32 v130, v130, v131
	v_cvt_pk_bf16_f32 v131, v122, v123
	v_cvt_pk_bf16_f32 v132, v132, v133
	s_nop 0
	v_cvt_pk_bf16_f32 v133, v138, v139
	global_store_dwordx4 v[116:117], v[130:133], off offset:2048
	global_store_dwordx4 v[136:137], v[118:121], off
	global_store_dwordx4 v[136:137], v[126:129], off offset:16
	s_nop 0
	v_lshl_add_u64 v[138:139], v[124:125], 0, v[150:151]
	s_nop 0
	s_waitcnt vmcnt(3)
	v_pk_add_f32 v[132:133], v[236:237], 1.0 op_sel_hi:[1,0]
	v_pk_add_f32 v[130:131], v[234:235], 1.0 op_sel_hi:[1,0]
	v_pk_add_f32 v[136:137], v[240:241], 1.0 op_sel_hi:[1,0]
	v_pk_add_f32 v[134:135], v[238:239], 1.0 op_sel_hi:[1,0]
	v_pk_fma_f32 v[120:121], v[120:121], v[132:133], v[246:247]
	v_pk_fma_f32 v[118:119], v[118:119], v[130:131], v[244:245]
	v_pk_fma_f32 v[122:123], v[128:129], v[136:137], v[254:255]
	v_pk_fma_f32 v[124:125], v[126:127], v[134:135], v[248:249]
	v_cvt_pk_bf16_f32 v118, v118, v119
	v_cvt_pk_bf16_f32 v119, v120, v121
	v_cvt_pk_bf16_f32 v121, v122, v123
	s_nop 0
	v_cvt_pk_bf16_f32 v120, v124, v125
	global_store_dwordx4 v[116:117], v[118:121], off offset:3072
	s_andn2_b64 exec, exec, s[16:17]
	s_cbranch_execz .LBB0_1214
